# low-rank in-projection tile: 8 k-steps of operand loads in flight with counted waits instead of one k-step per round trip
# speedup vs baseline: 1.0056x; 1.0027x over previous
.LBB0_230:
	v_mov_b32_e32 v10, v180
	s_lshl_b32 s0, s6, 5
	v_readlane_b32 s64, v254, 12
	s_ashr_i32 s1, s0, 31
	v_ashrrev_i32_e32 v11, 6, v10
	v_readlane_b32 s65, v254, 13
	v_readlane_b32 s66, v254, 14
	v_readlane_b32 s67, v254, 15
	s_lshl_b64 s[2:3], s[0:1], 13
	v_readlane_b32 s68, v254, 16
	v_lshlrev_b32_e32 v2, 9, v11
	v_readlane_b32 s52, v254, 60
	v_and_b32_e32 v12, 15, v10
	v_readlane_b32 s69, v254, 17
	s_add_u32 s2, s68, s2
	v_and_b32_e32 v0, 48, v10
	v_readlane_b32 s66, v253, 10
	v_readlane_b32 s67, v253, 11
	v_ashrrev_i32_e32 v3, 31, v2
	s_addc_u32 s3, s69, s3
	v_lshl_add_u64 v[4:5], s[66:67], 0, v[0:1]
	v_lshlrev_b64 v[2:3], 1, v[2:3]
	v_lshlrev_b32_e32 v22, 13, v12
	v_lshl_add_u64 v[8:9], v[4:5], 0, v[2:3]
	v_mov_b32_e32 v23, v1
	v_lshl_add_u64 v[4:5], s[2:3], 0, v[0:1]
	v_mov_b32_e32 v27, v1
	v_or_b32_e32 v26, 0x20000, v22
	v_lshl_add_u64 v[6:7], v[8:9], 0, v[22:23]
	v_lshl_add_u64 v[2:3], v[4:5], 0, v[2:3]
	v_lshl_add_u64 v[8:9], v[8:9], 0, v[26:27]
	v_lshl_add_u64 v[4:5], v[2:3], 0, v[22:23]
	v_lshl_add_u64 v[2:3], v[2:3], 0, v[26:27]
	s_movk_i32 s1, 0x400
	v_readlane_b32 s70, v254, 18
	v_readlane_b32 s71, v254, 19
	v_cmp_gt_i32_e32 vcc, s1, v10
	v_readlane_b32 s72, v254, 20
	v_readlane_b32 s73, v254, 21
	v_readlane_b32 s74, v254, 22
	v_readlane_b32 s75, v254, 23
	v_readlane_b32 s76, v254, 24
	v_readlane_b32 s77, v254, 25
	v_readlane_b32 s78, v254, 26
	v_readlane_b32 s79, v254, 27
	v_readlane_b32 s53, v254, 61
	v_readlane_b32 s54, v254, 62
	v_readlane_b32 s55, v254, 63
	v_readlane_b32 s56, v253, 0
	v_readlane_b32 s57, v253, 1
	v_readlane_b32 s58, v253, 2
	v_readlane_b32 s59, v253, 3
	v_readlane_b32 s60, v253, 4
	v_readlane_b32 s61, v253, 5
	v_readlane_b32 s62, v253, 6
	v_readlane_b32 s63, v253, 7
	v_readlane_b32 s64, v253, 8
	v_readlane_b32 s65, v253, 9
	global_load_dwordx4 v[40:43], v[6:7], off
	global_load_dwordx4 v[44:47], v[8:9], off
	global_load_dwordx4 v[48:51], v[4:5], off
	global_load_dwordx4 v[52:55], v[2:3], off
	global_load_dwordx4 v[56:59], v[6:7], off offset:64
	global_load_dwordx4 v[60:63], v[8:9], off offset:64
	global_load_dwordx4 v[64:67], v[4:5], off offset:64
	global_load_dwordx4 v[68:71], v[2:3], off offset:64
	global_load_dwordx4 v[72:75], v[6:7], off offset:128
	global_load_dwordx4 v[76:79], v[8:9], off offset:128
	global_load_dwordx4 v[80:83], v[4:5], off offset:128
	global_load_dwordx4 v[84:87], v[2:3], off offset:128
	global_load_dwordx4 v[88:91], v[6:7], off offset:192
	global_load_dwordx4 v[96:99], v[8:9], off offset:192
	global_load_dwordx4 v[100:103], v[4:5], off offset:192
	global_load_dwordx4 v[104:107], v[2:3], off offset:192
	global_load_dwordx4 v[108:111], v[6:7], off offset:256
	global_load_dwordx4 v[112:115], v[8:9], off offset:256
	global_load_dwordx4 v[116:119], v[4:5], off offset:256
	global_load_dwordx4 v[120:123], v[2:3], off offset:256
	global_load_dwordx4 v[124:127], v[6:7], off offset:320
	global_load_dwordx4 v[128:131], v[8:9], off offset:320
	global_load_dwordx4 v[132:135], v[4:5], off offset:320
	global_load_dwordx4 v[136:139], v[2:3], off offset:320
	global_load_dwordx4 v[140:143], v[6:7], off offset:384
	global_load_dwordx4 v[144:147], v[8:9], off offset:384
	global_load_dwordx4 v[148:151], v[4:5], off offset:384
	global_load_dwordx4 v[152:155], v[2:3], off offset:384
	global_load_dwordx4 v[156:159], v[6:7], off offset:448
	global_load_dwordx4 v[160:163], v[8:9], off offset:448
	global_load_dwordx4 v[164:167], v[4:5], off offset:448
	global_load_dwordx4 v[168:171], v[2:3], off offset:448
	s_waitcnt vmcnt(28)
	v_mfma_f32_16x16x32_bf16 v[16:19], v[40:43], v[48:51], 0
	v_mfma_f32_16x16x32_bf16 v[28:31], v[44:47], v[48:51], 0
	v_mfma_f32_16x16x32_bf16 v[32:35], v[40:43], v[52:55], 0
	v_mfma_f32_16x16x32_bf16 v[36:39], v[44:47], v[52:55], 0
	global_load_dwordx4 v[40:43], v[6:7], off offset:512
	global_load_dwordx4 v[44:47], v[8:9], off offset:512
	global_load_dwordx4 v[48:51], v[4:5], off offset:512
	global_load_dwordx4 v[52:55], v[2:3], off offset:512
	s_waitcnt vmcnt(28)
	v_mfma_f32_16x16x32_bf16 v[16:19], v[56:59], v[64:67], v[16:19]
	v_mfma_f32_16x16x32_bf16 v[28:31], v[60:63], v[64:67], v[28:31]
	v_mfma_f32_16x16x32_bf16 v[32:35], v[56:59], v[68:71], v[32:35]
	v_mfma_f32_16x16x32_bf16 v[36:39], v[60:63], v[68:71], v[36:39]
	global_load_dwordx4 v[56:59], v[6:7], off offset:576
	global_load_dwordx4 v[60:63], v[8:9], off offset:576
	global_load_dwordx4 v[64:67], v[4:5], off offset:576
	global_load_dwordx4 v[68:71], v[2:3], off offset:576
	s_waitcnt vmcnt(28)
	v_mfma_f32_16x16x32_bf16 v[16:19], v[72:75], v[80:83], v[16:19]
	v_mfma_f32_16x16x32_bf16 v[28:31], v[76:79], v[80:83], v[28:31]
	v_mfma_f32_16x16x32_bf16 v[32:35], v[72:75], v[84:87], v[32:35]
	v_mfma_f32_16x16x32_bf16 v[36:39], v[76:79], v[84:87], v[36:39]
	global_load_dwordx4 v[72:75], v[6:7], off offset:640
	global_load_dwordx4 v[76:79], v[8:9], off offset:640
	global_load_dwordx4 v[80:83], v[4:5], off offset:640
	global_load_dwordx4 v[84:87], v[2:3], off offset:640
	s_waitcnt vmcnt(28)
	v_mfma_f32_16x16x32_bf16 v[16:19], v[88:91], v[100:103], v[16:19]
	v_mfma_f32_16x16x32_bf16 v[28:31], v[96:99], v[100:103], v[28:31]
	v_mfma_f32_16x16x32_bf16 v[32:35], v[88:91], v[104:107], v[32:35]
	v_mfma_f32_16x16x32_bf16 v[36:39], v[96:99], v[104:107], v[36:39]
	global_load_dwordx4 v[88:91], v[6:7], off offset:704
	global_load_dwordx4 v[96:99], v[8:9], off offset:704
	global_load_dwordx4 v[100:103], v[4:5], off offset:704
	global_load_dwordx4 v[104:107], v[2:3], off offset:704
	s_waitcnt vmcnt(28)
	v_mfma_f32_16x16x32_bf16 v[16:19], v[108:111], v[116:119], v[16:19]
	v_mfma_f32_16x16x32_bf16 v[28:31], v[112:115], v[116:119], v[28:31]
	v_mfma_f32_16x16x32_bf16 v[32:35], v[108:111], v[120:123], v[32:35]
	v_mfma_f32_16x16x32_bf16 v[36:39], v[112:115], v[120:123], v[36:39]
	global_load_dwordx4 v[108:111], v[6:7], off offset:768
	global_load_dwordx4 v[112:115], v[8:9], off offset:768
	global_load_dwordx4 v[116:119], v[4:5], off offset:768
	global_load_dwordx4 v[120:123], v[2:3], off offset:768
	s_waitcnt vmcnt(28)
	v_mfma_f32_16x16x32_bf16 v[16:19], v[124:127], v[132:135], v[16:19]
	v_mfma_f32_16x16x32_bf16 v[28:31], v[128:131], v[132:135], v[28:31]
	v_mfma_f32_16x16x32_bf16 v[32:35], v[124:127], v[136:139], v[32:35]
	v_mfma_f32_16x16x32_bf16 v[36:39], v[128:131], v[136:139], v[36:39]
	global_load_dwordx4 v[124:127], v[6:7], off offset:832
	global_load_dwordx4 v[128:131], v[8:9], off offset:832
	global_load_dwordx4 v[132:135], v[4:5], off offset:832
	global_load_dwordx4 v[136:139], v[2:3], off offset:832
	s_waitcnt vmcnt(28)
	v_mfma_f32_16x16x32_bf16 v[16:19], v[140:143], v[148:151], v[16:19]
	v_mfma_f32_16x16x32_bf16 v[28:31], v[144:147], v[148:151], v[28:31]
	v_mfma_f32_16x16x32_bf16 v[32:35], v[140:143], v[152:155], v[32:35]
	v_mfma_f32_16x16x32_bf16 v[36:39], v[144:147], v[152:155], v[36:39]
	global_load_dwordx4 v[140:143], v[6:7], off offset:896
	global_load_dwordx4 v[144:147], v[8:9], off offset:896
	global_load_dwordx4 v[148:151], v[4:5], off offset:896
	global_load_dwordx4 v[152:155], v[2:3], off offset:896
	s_waitcnt vmcnt(28)
	v_mfma_f32_16x16x32_bf16 v[16:19], v[156:159], v[164:167], v[16:19]
	v_mfma_f32_16x16x32_bf16 v[28:31], v[160:163], v[164:167], v[28:31]
	v_mfma_f32_16x16x32_bf16 v[32:35], v[156:159], v[168:171], v[32:35]
	v_mfma_f32_16x16x32_bf16 v[36:39], v[160:163], v[168:171], v[36:39]
	global_load_dwordx4 v[156:159], v[6:7], off offset:960
	global_load_dwordx4 v[160:163], v[8:9], off offset:960
	global_load_dwordx4 v[164:167], v[4:5], off offset:960
	global_load_dwordx4 v[168:171], v[2:3], off offset:960
	s_waitcnt vmcnt(28)
	v_mfma_f32_16x16x32_bf16 v[16:19], v[40:43], v[48:51], v[16:19]
	v_mfma_f32_16x16x32_bf16 v[28:31], v[44:47], v[48:51], v[28:31]
	v_mfma_f32_16x16x32_bf16 v[32:35], v[40:43], v[52:55], v[32:35]
	v_mfma_f32_16x16x32_bf16 v[36:39], v[44:47], v[52:55], v[36:39]
	s_waitcnt vmcnt(24)
	v_mfma_f32_16x16x32_bf16 v[16:19], v[56:59], v[64:67], v[16:19]
	v_mfma_f32_16x16x32_bf16 v[28:31], v[60:63], v[64:67], v[28:31]
	v_mfma_f32_16x16x32_bf16 v[32:35], v[56:59], v[68:71], v[32:35]
	v_mfma_f32_16x16x32_bf16 v[36:39], v[60:63], v[68:71], v[36:39]
	s_waitcnt vmcnt(20)
	v_mfma_f32_16x16x32_bf16 v[16:19], v[72:75], v[80:83], v[16:19]
	v_mfma_f32_16x16x32_bf16 v[28:31], v[76:79], v[80:83], v[28:31]
	v_mfma_f32_16x16x32_bf16 v[32:35], v[72:75], v[84:87], v[32:35]
	v_mfma_f32_16x16x32_bf16 v[36:39], v[76:79], v[84:87], v[36:39]
	s_waitcnt vmcnt(16)
	v_mfma_f32_16x16x32_bf16 v[16:19], v[88:91], v[100:103], v[16:19]
	v_mfma_f32_16x16x32_bf16 v[28:31], v[96:99], v[100:103], v[28:31]
	v_mfma_f32_16x16x32_bf16 v[32:35], v[88:91], v[104:107], v[32:35]
	v_mfma_f32_16x16x32_bf16 v[36:39], v[96:99], v[104:107], v[36:39]
	s_waitcnt vmcnt(12)
	v_mfma_f32_16x16x32_bf16 v[16:19], v[108:111], v[116:119], v[16:19]
	v_mfma_f32_16x16x32_bf16 v[28:31], v[112:115], v[116:119], v[28:31]
	v_mfma_f32_16x16x32_bf16 v[32:35], v[108:111], v[120:123], v[32:35]
	v_mfma_f32_16x16x32_bf16 v[36:39], v[112:115], v[120:123], v[36:39]
	s_waitcnt vmcnt(8)
	v_mfma_f32_16x16x32_bf16 v[16:19], v[124:127], v[132:135], v[16:19]
	v_mfma_f32_16x16x32_bf16 v[28:31], v[128:131], v[132:135], v[28:31]
	v_mfma_f32_16x16x32_bf16 v[32:35], v[124:127], v[136:139], v[32:35]
	v_mfma_f32_16x16x32_bf16 v[36:39], v[128:131], v[136:139], v[36:39]
	s_waitcnt vmcnt(4)
	v_mfma_f32_16x16x32_bf16 v[16:19], v[140:143], v[148:151], v[16:19]
	v_mfma_f32_16x16x32_bf16 v[28:31], v[144:147], v[148:151], v[28:31]
	v_mfma_f32_16x16x32_bf16 v[32:35], v[140:143], v[152:155], v[32:35]
	v_mfma_f32_16x16x32_bf16 v[36:39], v[144:147], v[152:155], v[36:39]
	s_waitcnt vmcnt(0)
	v_mfma_f32_16x16x32_bf16 v[16:19], v[156:159], v[164:167], v[16:19]
	v_mfma_f32_16x16x32_bf16 v[28:31], v[160:163], v[164:167], v[28:31]
	v_mfma_f32_16x16x32_bf16 v[32:35], v[156:159], v[168:171], v[32:35]
	v_mfma_f32_16x16x32_bf16 v[36:39], v[160:163], v[168:171], v[36:39]
	v_lshl_add_u32 v6, v11, 12, 0
	v_lshlrev_b32_e32 v7, 7, v12
	v_add3_u32 v0, v6, v7, v0
	s_nop 7
	s_nop 7
	ds_write_b128 v0, v[16:19]
	ds_write_b128 v0, v[28:31] offset:64
	ds_write_b128 v0, v[32:35] offset:2048
	ds_write_b128 v0, v[36:39] offset:2112
	s_waitcnt lgkmcnt(0)
	s_barrier
	s_and_saveexec_b64 s[2:3], vcc
	s_cbranch_execz .LBB0_229
	v_and_b32_e32 v0, 31, v10
	v_lshl_add_u32 v2, v10, 2, 0
	s_mov_b64 s[4:5], 0
	v_lshlrev_b32_e32 v0, 1, v0

.LBB0_940:
	s_lshl_b32 s2, s11, 5
	v_mov_b32_e32 v2, v180
	s_ashr_i32 s3, s2, 31
	v_readlane_b32 s64, v254, 12
	s_lshl_b64 s[4:5], s[2:3], 13
	v_ashrrev_i32_e32 v3, 6, v2
	v_readlane_b32 s68, v254, 16
	v_readlane_b32 s69, v254, 17
	s_add_u32 s4, s68, s4
	v_lshlrev_b32_e32 v4, 9, v3
	v_and_b32_e32 v56, 15, v2
	s_addc_u32 s5, s69, s5
	v_and_b32_e32 v0, 48, v2
	v_ashrrev_i32_e32 v5, 31, v4
	v_lshl_add_u64 v[6:7], s[0:1], 0, v[0:1]
	v_lshlrev_b64 v[8:9], 1, v[4:5]
	v_lshlrev_b32_e32 v14, 13, v56
	v_lshl_add_u64 v[10:11], s[4:5], 0, v[0:1]
	v_lshl_add_u64 v[12:13], v[6:7], 0, v[8:9]
	v_mov_b32_e32 v15, v1
	v_lshl_add_u64 v[28:29], v[10:11], 0, v[8:9]
	v_mov_b32_e32 v31, v1
	v_or_b32_e32 v30, 0x20000, v14
	v_lshl_add_u64 v[48:49], v[12:13], 0, v[14:15]
	v_lshl_add_u64 v[50:51], v[28:29], 0, v[14:15]
	v_lshl_add_u64 v[52:53], v[12:13], 0, v[30:31]
	v_lshl_add_u64 v[54:55], v[28:29], 0, v[30:31]
	v_lshl_add_u32 v3, v3, 12, 0
	v_readlane_b32 s70, v254, 18
	v_readlane_b32 s71, v254, 19
	v_cmp_gt_i32_e32 vcc, s8, v2
	v_readlane_b32 s65, v254, 13
	v_readlane_b32 s66, v254, 14
	v_readlane_b32 s67, v254, 15
	v_readlane_b32 s72, v254, 20
	v_readlane_b32 s73, v254, 21
	v_readlane_b32 s74, v254, 22
	v_readlane_b32 s75, v254, 23
	v_readlane_b32 s76, v254, 24
	v_readlane_b32 s77, v254, 25
	v_readlane_b32 s78, v254, 26
	v_readlane_b32 s79, v254, 27
	global_load_dwordx4 v[44:47], v[48:49], off
	global_load_dwordx4 v[60:63], v[52:53], off
	global_load_dwordx4 v[64:67], v[50:51], off
	global_load_dwordx4 v[68:71], v[54:55], off
	global_load_dwordx4 v[72:75], v[48:49], off offset:64
	global_load_dwordx4 v[76:79], v[52:53], off offset:64
	global_load_dwordx4 v[80:83], v[50:51], off offset:64
	global_load_dwordx4 v[84:87], v[54:55], off offset:64
	global_load_dwordx4 v[88:91], v[48:49], off offset:128
	global_load_dwordx4 v[96:99], v[52:53], off offset:128
	global_load_dwordx4 v[100:103], v[50:51], off offset:128
	global_load_dwordx4 v[104:107], v[54:55], off offset:128
	global_load_dwordx4 v[108:111], v[48:49], off offset:192
	global_load_dwordx4 v[112:115], v[52:53], off offset:192
	global_load_dwordx4 v[116:119], v[50:51], off offset:192
	global_load_dwordx4 v[120:123], v[54:55], off offset:192
	global_load_dwordx4 v[124:127], v[48:49], off offset:256
	global_load_dwordx4 v[128:131], v[52:53], off offset:256
	global_load_dwordx4 v[132:135], v[50:51], off offset:256
	global_load_dwordx4 v[136:139], v[54:55], off offset:256
	global_load_dwordx4 v[140:143], v[48:49], off offset:320
	global_load_dwordx4 v[144:147], v[52:53], off offset:320
	global_load_dwordx4 v[148:151], v[50:51], off offset:320
	global_load_dwordx4 v[152:155], v[54:55], off offset:320
	global_load_dwordx4 v[156:159], v[48:49], off offset:384
	global_load_dwordx4 v[160:163], v[52:53], off offset:384
	global_load_dwordx4 v[164:167], v[50:51], off offset:384
	global_load_dwordx4 v[168:171], v[54:55], off offset:384
	global_load_dwordx4 v[172:175], v[48:49], off offset:448
	global_load_dwordx4 v[176:179], v[52:53], off offset:448
	global_load_dwordx4 v[184:187], v[50:51], off offset:448
	global_load_dwordx4 v[188:191], v[54:55], off offset:448
	s_waitcnt vmcnt(28)
	v_mfma_f32_16x16x32_bf16 v[24:27], v[44:47], v[64:67], 0
	v_mfma_f32_16x16x32_bf16 v[32:35], v[60:63], v[64:67], 0
	v_mfma_f32_16x16x32_bf16 v[36:39], v[44:47], v[68:71], 0
	v_mfma_f32_16x16x32_bf16 v[40:43], v[60:63], v[68:71], 0
	global_load_dwordx4 v[44:47], v[48:49], off offset:512
	global_load_dwordx4 v[60:63], v[52:53], off offset:512
	global_load_dwordx4 v[64:67], v[50:51], off offset:512
	global_load_dwordx4 v[68:71], v[54:55], off offset:512
	s_waitcnt vmcnt(28)
	v_mfma_f32_16x16x32_bf16 v[24:27], v[72:75], v[80:83], v[24:27]
	v_mfma_f32_16x16x32_bf16 v[32:35], v[76:79], v[80:83], v[32:35]
	v_mfma_f32_16x16x32_bf16 v[36:39], v[72:75], v[84:87], v[36:39]
	v_mfma_f32_16x16x32_bf16 v[40:43], v[76:79], v[84:87], v[40:43]
	global_load_dwordx4 v[72:75], v[48:49], off offset:576
	global_load_dwordx4 v[76:79], v[52:53], off offset:576
	global_load_dwordx4 v[80:83], v[50:51], off offset:576
	global_load_dwordx4 v[84:87], v[54:55], off offset:576
	s_waitcnt vmcnt(28)
	v_mfma_f32_16x16x32_bf16 v[24:27], v[88:91], v[100:103], v[24:27]
	v_mfma_f32_16x16x32_bf16 v[32:35], v[96:99], v[100:103], v[32:35]
	v_mfma_f32_16x16x32_bf16 v[36:39], v[88:91], v[104:107], v[36:39]
	v_mfma_f32_16x16x32_bf16 v[40:43], v[96:99], v[104:107], v[40:43]
	global_load_dwordx4 v[88:91], v[48:49], off offset:640
	global_load_dwordx4 v[96:99], v[52:53], off offset:640
	global_load_dwordx4 v[100:103], v[50:51], off offset:640
	global_load_dwordx4 v[104:107], v[54:55], off offset:640
	s_waitcnt vmcnt(28)
	v_mfma_f32_16x16x32_bf16 v[24:27], v[108:111], v[116:119], v[24:27]
	v_mfma_f32_16x16x32_bf16 v[32:35], v[112:115], v[116:119], v[32:35]
	v_mfma_f32_16x16x32_bf16 v[36:39], v[108:111], v[120:123], v[36:39]
	v_mfma_f32_16x16x32_bf16 v[40:43], v[112:115], v[120:123], v[40:43]
	global_load_dwordx4 v[108:111], v[48:49], off offset:704
	global_load_dwordx4 v[112:115], v[52:53], off offset:704
	global_load_dwordx4 v[116:119], v[50:51], off offset:704
	global_load_dwordx4 v[120:123], v[54:55], off offset:704
	s_waitcnt vmcnt(28)
	v_mfma_f32_16x16x32_bf16 v[24:27], v[124:127], v[132:135], v[24:27]
	v_mfma_f32_16x16x32_bf16 v[32:35], v[128:131], v[132:135], v[32:35]
	v_mfma_f32_16x16x32_bf16 v[36:39], v[124:127], v[136:139], v[36:39]
	v_mfma_f32_16x16x32_bf16 v[40:43], v[128:131], v[136:139], v[40:43]
	global_load_dwordx4 v[124:127], v[48:49], off offset:768
	global_load_dwordx4 v[128:131], v[52:53], off offset:768
	global_load_dwordx4 v[132:135], v[50:51], off offset:768
	global_load_dwordx4 v[136:139], v[54:55], off offset:768
	s_waitcnt vmcnt(28)
	v_mfma_f32_16x16x32_bf16 v[24:27], v[140:143], v[148:151], v[24:27]
	v_mfma_f32_16x16x32_bf16 v[32:35], v[144:147], v[148:151], v[32:35]
	v_mfma_f32_16x16x32_bf16 v[36:39], v[140:143], v[152:155], v[36:39]
	v_mfma_f32_16x16x32_bf16 v[40:43], v[144:147], v[152:155], v[40:43]
	global_load_dwordx4 v[140:143], v[48:49], off offset:832
	global_load_dwordx4 v[144:147], v[52:53], off offset:832
	global_load_dwordx4 v[148:151], v[50:51], off offset:832
	global_load_dwordx4 v[152:155], v[54:55], off offset:832
	s_waitcnt vmcnt(28)
	v_mfma_f32_16x16x32_bf16 v[24:27], v[156:159], v[164:167], v[24:27]
	v_mfma_f32_16x16x32_bf16 v[32:35], v[160:163], v[164:167], v[32:35]
	v_mfma_f32_16x16x32_bf16 v[36:39], v[156:159], v[168:171], v[36:39]
	v_mfma_f32_16x16x32_bf16 v[40:43], v[160:163], v[168:171], v[40:43]
	global_load_dwordx4 v[156:159], v[48:49], off offset:896
	global_load_dwordx4 v[160:163], v[52:53], off offset:896
	global_load_dwordx4 v[164:167], v[50:51], off offset:896
	global_load_dwordx4 v[168:171], v[54:55], off offset:896
	s_waitcnt vmcnt(28)
	v_mfma_f32_16x16x32_bf16 v[24:27], v[172:175], v[184:187], v[24:27]
	v_mfma_f32_16x16x32_bf16 v[32:35], v[176:179], v[184:187], v[32:35]
	v_mfma_f32_16x16x32_bf16 v[36:39], v[172:175], v[188:191], v[36:39]
	v_mfma_f32_16x16x32_bf16 v[40:43], v[176:179], v[188:191], v[40:43]
	global_load_dwordx4 v[172:175], v[48:49], off offset:960
	global_load_dwordx4 v[176:179], v[52:53], off offset:960
	global_load_dwordx4 v[184:187], v[50:51], off offset:960
	global_load_dwordx4 v[188:191], v[54:55], off offset:960
	s_waitcnt vmcnt(28)
	v_mfma_f32_16x16x32_bf16 v[24:27], v[44:47], v[64:67], v[24:27]
	v_mfma_f32_16x16x32_bf16 v[32:35], v[60:63], v[64:67], v[32:35]
	v_mfma_f32_16x16x32_bf16 v[36:39], v[44:47], v[68:71], v[36:39]
	v_mfma_f32_16x16x32_bf16 v[40:43], v[60:63], v[68:71], v[40:43]
	s_waitcnt vmcnt(24)
	v_mfma_f32_16x16x32_bf16 v[24:27], v[72:75], v[80:83], v[24:27]
	v_mfma_f32_16x16x32_bf16 v[32:35], v[76:79], v[80:83], v[32:35]
	v_mfma_f32_16x16x32_bf16 v[36:39], v[72:75], v[84:87], v[36:39]
	v_mfma_f32_16x16x32_bf16 v[40:43], v[76:79], v[84:87], v[40:43]
	s_waitcnt vmcnt(20)
	v_mfma_f32_16x16x32_bf16 v[24:27], v[88:91], v[100:103], v[24:27]
	v_mfma_f32_16x16x32_bf16 v[32:35], v[96:99], v[100:103], v[32:35]
	v_mfma_f32_16x16x32_bf16 v[36:39], v[88:91], v[104:107], v[36:39]
	v_mfma_f32_16x16x32_bf16 v[40:43], v[96:99], v[104:107], v[40:43]
	s_waitcnt vmcnt(16)
	v_mfma_f32_16x16x32_bf16 v[24:27], v[108:111], v[116:119], v[24:27]
	v_mfma_f32_16x16x32_bf16 v[32:35], v[112:115], v[116:119], v[32:35]
	v_mfma_f32_16x16x32_bf16 v[36:39], v[108:111], v[120:123], v[36:39]
	v_mfma_f32_16x16x32_bf16 v[40:43], v[112:115], v[120:123], v[40:43]
	s_waitcnt vmcnt(12)
	v_mfma_f32_16x16x32_bf16 v[24:27], v[124:127], v[132:135], v[24:27]
	v_mfma_f32_16x16x32_bf16 v[32:35], v[128:131], v[132:135], v[32:35]
	v_mfma_f32_16x16x32_bf16 v[36:39], v[124:127], v[136:139], v[36:39]
	v_mfma_f32_16x16x32_bf16 v[40:43], v[128:131], v[136:139], v[40:43]
	s_waitcnt vmcnt(8)
	v_mfma_f32_16x16x32_bf16 v[24:27], v[140:143], v[148:151], v[24:27]
	v_mfma_f32_16x16x32_bf16 v[32:35], v[144:147], v[148:151], v[32:35]
	v_mfma_f32_16x16x32_bf16 v[36:39], v[140:143], v[152:155], v[36:39]
	v_mfma_f32_16x16x32_bf16 v[40:43], v[144:147], v[152:155], v[40:43]
	s_waitcnt vmcnt(4)
	v_mfma_f32_16x16x32_bf16 v[24:27], v[156:159], v[164:167], v[24:27]
	v_mfma_f32_16x16x32_bf16 v[32:35], v[160:163], v[164:167], v[32:35]
	v_mfma_f32_16x16x32_bf16 v[36:39], v[156:159], v[168:171], v[36:39]
	v_mfma_f32_16x16x32_bf16 v[40:43], v[160:163], v[168:171], v[40:43]
	s_waitcnt vmcnt(0)
	v_mfma_f32_16x16x32_bf16 v[24:27], v[172:175], v[184:187], v[24:27]
	v_mfma_f32_16x16x32_bf16 v[32:35], v[176:179], v[184:187], v[32:35]
	v_mfma_f32_16x16x32_bf16 v[36:39], v[172:175], v[188:191], v[36:39]
	v_mfma_f32_16x16x32_bf16 v[40:43], v[176:179], v[188:191], v[40:43]
	v_lshlrev_b32_e32 v20, 7, v56
	v_add3_u32 v0, v3, v20, v0
	s_nop 7
	s_nop 7
	ds_write_b128 v0, v[24:27]
	ds_write_b128 v0, v[32:35] offset:64
	ds_write_b128 v0, v[36:39] offset:2048
	ds_write_b128 v0, v[40:43] offset:2112
	s_waitcnt lgkmcnt(0)
	s_barrier
	s_and_saveexec_b64 s[4:5], vcc
	s_cbranch_execz .LBB0_939
	v_and_b32_e32 v0, 31, v2
	v_lshl_add_u32 v3, v2, 2, 0
	s_mov_b64 s[6:7], 0
	v_lshlrev_b32_e32 v0, 1, v0
